# v8: + P9 residual epilogue counted waits
# baseline (speedup 1.0000x reference)
; #define LAS __attribute__((address_space(3)))
; __device__ __forceinline__ unsigned pk_bf16(float lo, float hi) { unsigned r; asm volatile("v_cvt_pk_bf16_f32 %0, %1, %2" : "=v"(r) : "v"(lo), "v"(hi)); return r; }
; __device__ __forceinline__ f32x4 mfma16(bf16x8 a, bf16x8 b, f32x4 c) { return __builtin_amdgcn_mfma_f32_16x16x32_bf16(a, b, c, 0, 0, 0); }
; __device__ __forceinline__ void gla_prep(const PrepRegs& R, LAS unsigned char* lds, int wave, int fr, int fq) {
;     ...
;     for (int q = 0; q < 3; ++q) { const int tile = wave * 3 + q, mi = tile / 6, ni = tile % 6, dir = ni / 3, c = (ni % 3) * 16 + fr;
;         const f32x4 acc = mfma16(as_bf8(R.ga[q]), as_bf8(R.bw[q]), (f32x4){0.f, 0.f, 0.f, 0.f});
;         float g[4];
; #pragma unroll
;         for (int i = 0; i < 4; ++i) { const float sv = acc[i] + R.bias[q]; g[i] = (fminf(sv, 0.f) - __logf(1.f + __expf(-fabsf(sv)))) * (1.0f / 16.0f); }
;         u32x2 w2; w2.x = pk_bf16(g[0], g[1]); w2.y = pk_bf16(g[2], g[3]);
;         *(LAS u32x2*)(lds + GL_GT + (dir * 48 + c) * 144 + (mi * 16 + fq * 4) * 2) = w2; }
.LBB0_698:
	s_or_b64 exec, exec, s[4:5]
	s_waitcnt vmcnt(1)
	v_cvt_pk_bf16_f32 v30, v113, v112
	v_cvt_pk_bf16_f32 v31, v115, v114
	v_cvt_pk_bf16_f32 v32, v117, v116
	v_cvt_pk_bf16_f32 v33, v119, v118
	v_and_b32_e32 v30, v140, v30
	v_and_b32_e32 v31, v140, v31
	v_and_b32_e32 v32, v140, v32
	v_and_b32_e32 v33, v140, v33
	v_cvt_pk_bf16_f32 v34, v121, v120
	v_cvt_pk_bf16_f32 v35, v123, v122
	v_cvt_pk_bf16_f32 v36, v125, v124
	v_cvt_pk_bf16_f32 v37, v127, v126
	v_and_b32_e32 v34, v141, v34
	v_and_b32_e32 v35, v141, v35
	v_and_b32_e32 v36, v141, v36
	v_and_b32_e32 v37, v141, v37
	v_cvt_pk_bf16_f32 v38, v133, v132
	v_cvt_pk_bf16_f32 v39, v135, v134
	v_cvt_pk_bf16_f32 v40, v137, v136
	v_cvt_pk_bf16_f32 v41, v139, v138
	v_and_b32_e32 v38, v142, v38
	v_and_b32_e32 v39, v142, v39
	v_and_b32_e32 v40, v142, v40
	v_and_b32_e32 v41, v142, v41
	v_mfma_f32_16x16x32_bf16 v[18:21], v[18:21], v[30:33], 0
	s_barrier
	v_or_b32_e32 v33, 2, v61
	v_or_b32_e32 v47, 34, v61
	s_waitcnt vmcnt(4)
	s_nop 3
	v_add_f32_e32 v18, v78, v18
	v_mul_f32_e64 v30, |v18|, s33
	v_exp_f32_e32 v30, v30
	v_add_f32_e32 v19, v78, v19
	v_min_f32_e32 v18, 0, v18
	v_add_f32_e32 v20, v78, v20
	v_add_f32_e32 v30, 1.0, v30
	v_cmp_gt_f32_e64 s[18:19], s68, v30
	v_add_f32_e32 v21, v78, v21
	v_or_b32_e32 v58, 37, v61
	v_cndmask_b32_e64 v31, 0, 32, s[18:19]
	v_ldexp_f32 v30, v30, v31
	v_log_f32_e32 v30, v30
	v_mul_f32_e64 v31, |v19|, s33
	v_exp_f32_e32 v31, v31
	v_min_f32_e32 v19, 0, v19
	v_mul_f32_e32 v32, 0x3f317217, v30
	v_fma_f32 v32, v30, s2, -v32
	v_fmac_f32_e32 v32, 0x3377d1cf, v30
	v_fmac_f32_e32 v32, 0x3f317217, v30
	v_cmp_lt_f32_e64 s[20:21], |v30|, s83
	v_add_f32_e32 v31, 1.0, v31
	s_nop 0
	v_cndmask_b32_e64 v30, v30, v32, s[20:21]
	v_cndmask_b32_e64 v32, 0, v241, s[18:19]
	v_cmp_gt_f32_e64 s[18:19], s68, v31
	v_sub_f32_e32 v30, v30, v32
	v_sub_f32_e32 v18, v18, v30
	v_cndmask_b32_e64 v32, 0, 32, s[18:19]
	v_ldexp_f32 v31, v31, v32
	v_log_f32_e32 v31, v31
	v_mul_f32_e64 v32, |v20|, s33
	v_exp_f32_e32 v32, v32
	v_min_f32_e32 v20, 0, v20
	v_mul_f32_e32 v30, 0x3f317217, v31
	v_fma_f32 v30, v31, s2, -v30
	v_fmac_f32_e32 v30, 0x3377d1cf, v31
	v_fmac_f32_e32 v30, 0x3f317217, v31
	v_cmp_lt_f32_e64 s[20:21], |v31|, s83
	v_mul_f32_e32 v18, 0x3d800000, v18
	s_nop 0
	v_cndmask_b32_e64 v30, v31, v30, s[20:21]
	v_cndmask_b32_e64 v31, 0, v241, s[18:19]
	v_sub_f32_e32 v30, v30, v31
	v_add_f32_e32 v31, 1.0, v32
	v_cmp_gt_f32_e64 s[18:19], s68, v31
	v_sub_f32_e32 v19, v19, v30
	v_mul_f32_e32 v19, 0x3d800000, v19
	v_cndmask_b32_e64 v32, 0, 32, s[18:19]
	v_ldexp_f32 v31, v31, v32
	v_log_f32_e32 v31, v31
	v_mul_f32_e64 v32, |v21|, s33
	v_exp_f32_e32 v32, v32
	v_min_f32_e32 v21, 0, v21
	v_mul_f32_e32 v30, 0x3f317217, v31
	v_fma_f32 v30, v31, s2, -v30
	v_fmac_f32_e32 v30, 0x3377d1cf, v31
	v_fmac_f32_e32 v30, 0x3f317217, v31
	v_cmp_lt_f32_e64 s[20:21], |v31|, s83
	s_nop 1
	v_cndmask_b32_e64 v30, v31, v30, s[20:21]
	v_cndmask_b32_e64 v31, 0, v241, s[18:19]
	v_sub_f32_e32 v30, v30, v31
	v_add_f32_e32 v31, 1.0, v32
	v_cmp_gt_f32_e64 s[18:19], s68, v31
	v_sub_f32_e32 v20, v20, v30
	v_mul_f32_e32 v20, 0x3d800000, v20
	v_cndmask_b32_e64 v32, 0, 32, s[18:19]
	v_ldexp_f32 v31, v31, v32
	v_log_f32_e32 v31, v31
	v_mad_i32_i24 v32, v70, 48, v52
	v_or_b32_e32 v52, 35, v61
	v_mul_f32_e32 v30, 0x3f317217, v31
	v_fma_f32 v30, v31, s2, -v30
	v_fmac_f32_e32 v30, 0x3377d1cf, v31
	v_fmac_f32_e32 v30, 0x3f317217, v31
	v_cmp_lt_f32_e64 s[20:21], |v31|, s83
	s_nop 1
	v_cndmask_b32_e64 v30, v31, v30, s[20:21]
	v_cndmask_b32_e64 v31, 0, v241, s[18:19]
	v_sub_f32_e32 v30, v30, v31
	v_sub_f32_e32 v21, v21, v30
	v_mul_f32_e32 v21, 0x3d800000, v21
	v_cvt_pk_bf16_f32 v30, v18, v19
	v_cvt_pk_bf16_f32 v31, v20, v21
	s_waitcnt vmcnt(3)
	v_mfma_f32_16x16x32_bf16 v[18:21], v[22:25], v[34:37], 0
	v_mul_lo_u32 v23, v32, s55
	v_add_u32_e32 v23, 0, v23
	v_lshlrev_b32_e32 v24, 5, v75
	v_add3_u32 v23, v23, v24, v61
	ds_write_b64 v23, v[30:31]
	s_waitcnt vmcnt(2)
	s_nop 1
	v_add_f32_e32 v18, v79, v18
	v_mul_f32_e64 v22, |v18|, s33
	v_exp_f32_e32 v22, v22
	v_add_f32_e32 v19, v79, v19
	v_mul_f32_e64 v24, |v19|, s33
	v_exp_f32_e32 v24, v24
	v_add_f32_e32 v22, 1.0, v22
	v_cmp_gt_f32_e64 s[18:19], s68, v22
	v_min_f32_e32 v18, 0, v18
	v_add_f32_e32 v20, v79, v20
	v_cndmask_b32_e64 v25, 0, 32, s[18:19]
	v_ldexp_f32 v22, v22, v25
	v_log_f32_e32 v22, v22
	v_min_f32_e32 v19, 0, v19
	v_add_f32_e32 v21, v79, v21
	v_or_b32_e32 v32, 1, v61
	v_mul_f32_e32 v23, 0x3f317217, v22
	v_fma_f32 v23, v22, s2, -v23
	v_fmac_f32_e32 v23, 0x3377d1cf, v22
	v_fmac_f32_e32 v23, 0x3f317217, v22
	v_cmp_lt_f32_e64 s[20:21], |v22|, s83
	v_or_b32_e32 v34, 3, v61
	v_or_b32_e32 v35, 4, v61
	v_cndmask_b32_e64 v22, v22, v23, s[20:21]
	v_cndmask_b32_e64 v23, 0, v241, s[18:19]
	v_sub_f32_e32 v22, v22, v23
	v_add_f32_e32 v23, 1.0, v24
	v_cmp_gt_f32_e64 s[18:19], s68, v23
	v_sub_f32_e32 v18, v18, v22
	v_mul_f32_e32 v18, 0x3d800000, v18
	v_cndmask_b32_e64 v24, 0, 32, s[18:19]
	v_ldexp_f32 v23, v23, v24
	v_log_f32_e32 v23, v23
	v_mul_f32_e64 v24, |v20|, s33
	v_exp_f32_e32 v24, v24
	v_min_f32_e32 v20, 0, v20
	v_mul_f32_e32 v22, 0x3f317217, v23
	v_fma_f32 v22, v23, s2, -v22
	v_fmac_f32_e32 v22, 0x3377d1cf, v23
	v_fmac_f32_e32 v22, 0x3f317217, v23
	v_cmp_lt_f32_e64 s[20:21], |v23|, s83
	v_or_b32_e32 v36, 5, v61
	v_or_b32_e32 v37, 6, v61
	v_cndmask_b32_e64 v22, v23, v22, s[20:21]
	v_cndmask_b32_e64 v23, 0, v241, s[18:19]
	v_sub_f32_e32 v22, v22, v23
	v_add_f32_e32 v23, 1.0, v24
	v_cmp_gt_f32_e64 s[18:19], s68, v23
	v_sub_f32_e32 v19, v19, v22
	v_mul_f32_e32 v19, 0x3d800000, v19
	v_cndmask_b32_e64 v24, 0, 32, s[18:19]
	v_ldexp_f32 v23, v23, v24
	v_log_f32_e32 v23, v23
	v_mul_f32_e64 v24, |v21|, s33
	v_exp_f32_e32 v24, v24
	v_min_f32_e32 v21, 0, v21
	v_mul_f32_e32 v22, 0x3f317217, v23
	v_fma_f32 v22, v23, s2, -v22
	v_fmac_f32_e32 v22, 0x3377d1cf, v23
	v_fmac_f32_e32 v22, 0x3f317217, v23
	v_cmp_lt_f32_e64 s[20:21], |v23|, s83
	s_nop 1
	v_cndmask_b32_e64 v22, v23, v22, s[20:21]
	v_cndmask_b32_e64 v23, 0, v241, s[18:19]
	v_sub_f32_e32 v22, v22, v23
	v_add_f32_e32 v23, 1.0, v24
	v_cmp_gt_f32_e64 s[18:19], s68, v23
	v_sub_f32_e32 v20, v20, v22
	v_mul_f32_e32 v20, 0x3d800000, v20
	v_cndmask_b32_e64 v24, 0, 32, s[18:19]
	v_ldexp_f32 v23, v23, v24
	v_log_f32_e32 v23, v23
	v_mad_i32_i24 v24, v66, 48, v54
	v_mul_lo_u32 v24, v24, s55
	v_add_u32_e32 v24, 0, v24
	v_mul_f32_e32 v22, 0x3f317217, v23
	v_fma_f32 v22, v23, s2, -v22
	v_fmac_f32_e32 v22, 0x3377d1cf, v23
	v_fmac_f32_e32 v22, 0x3f317217, v23
	v_cmp_lt_f32_e64 s[20:21], |v23|, s83
	s_nop 1
	v_cndmask_b32_e64 v22, v23, v22, s[20:21]
	v_cndmask_b32_e64 v23, 0, v241, s[18:19]
	v_sub_f32_e32 v22, v22, v23
	v_sub_f32_e32 v21, v21, v22
	v_mul_f32_e32 v21, 0x3d800000, v21
	v_cvt_pk_bf16_f32 v22, v18, v19
	v_cvt_pk_bf16_f32 v23, v20, v21
	s_waitcnt vmcnt(1)
; #define LAS __attribute__((address_space(3)))
; __device__ __forceinline__ unsigned pk_bf16(float lo, float hi) { unsigned r; asm volatile("v_cvt_pk_bf16_f32 %0, %1, %2" : "=v"(r) : "v"(lo), "v"(hi)); return r; }
; __device__ __forceinline__ f32x4 mfma16(bf16x8 a, bf16x8 b, f32x4 c) { return __builtin_amdgcn_mfma_f32_16x16x32_bf16(a, b, c, 0, 0, 0); }
; __device__ __forceinline__ void gla_prep(const PrepRegs& R, LAS unsigned char* lds, int wave, int fr, int fq) {
;     ...
;     for (int q = 0; q < 3; ++q) { const int tile = wave * 3 + q, mi = tile / 6, ni = tile % 6, dir = ni / 3, c = (ni % 3) * 16 + fr;
;         const f32x4 acc = mfma16(as_bf8(R.ga[q]), as_bf8(R.bw[q]), (f32x4){0.f, 0.f, 0.f, 0.f});
;         float g[4];
; #pragma unroll
;         for (int i = 0; i < 4; ++i) { const float sv = acc[i] + R.bias[q]; g[i] = (fminf(sv, 0.f) - __logf(1.f + __expf(-fabsf(sv)))) * (1.0f / 16.0f); }
;         u32x2 w2; w2.x = pk_bf16(g[0], g[1]); w2.y = pk_bf16(g[2], g[3]);
;         *(LAS u32x2*)(lds + GL_GT + (dir * 48 + c) * 144 + (mi * 16 + fq * 4) * 2) = w2; }
;     __syncthreads();
; #pragma unroll
;     for (int q = 0; q < 3; ++q) { const int tile = wave * 3 + q, mi = tile / 6, ni = tile % 6, dir = ni / 3;
;         f32x4 acc = (f32x4){0.f, 0.f, 0.f, 0.f};
; #pragma unroll
;         for (int kk = 0; kk < 2; ++kk) { const int t = mi * 16 + fr; bf16x8 tri;
; #pragma unroll
;             for (int e = 0; e < 8; ++e) { const int sidx = kk * 32 + fq * 8 + e; tri[e] = (dir ? (sidx >= t) : (sidx <= t)) ? (short)0x3F80 : (short)0; }
	v_mfma_f32_16x16x32_bf16 v[18:21], v[26:29], v[38:41], 0
	v_lshlrev_b32_e32 v26, 5, v76
	v_add3_u32 v24, v24, v26, v61
	ds_write_b64 v24, v[22:23]
	v_or_b32_e32 v38, 7, v61
	v_or_b32_e32 v39, 32, v61
	s_waitcnt vmcnt(0)
	s_nop 1
	v_add_f32_e32 v18, v80, v18
	v_mul_f32_e64 v25, |v18|, s33
	v_exp_f32_e32 v25, v25
	v_add_f32_e32 v19, v80, v19
	v_mul_f32_e64 v23, |v19|, s33
	v_exp_f32_e32 v23, v23
	v_add_f32_e32 v25, 1.0, v25
	v_cmp_gt_f32_e64 s[18:19], s68, v25
	v_min_f32_e32 v18, 0, v18
	v_add_f32_e32 v23, 1.0, v23
	v_cndmask_b32_e64 v27, 0, 32, s[18:19]
	v_ldexp_f32 v25, v25, v27
	v_log_f32_e32 v25, v25
	v_cndmask_b32_e64 v24, 0, v241, s[18:19]
	v_cmp_gt_f32_e64 s[18:19], s68, v23
	v_add_f32_e32 v20, v80, v20
	v_mul_f32_e32 v22, 0x3f317217, v25
	v_fma_f32 v22, v25, s2, -v22
	v_fmac_f32_e32 v22, 0x3377d1cf, v25
	v_fmac_f32_e32 v22, 0x3f317217, v25
	v_cmp_lt_f32_e64 s[20:21], |v25|, s83
	v_min_f32_e32 v19, 0, v19
	v_add_f32_e32 v21, v80, v21
	v_cndmask_b32_e64 v22, v25, v22, s[20:21]
	v_sub_f32_e32 v22, v22, v24
	v_cndmask_b32_e64 v24, 0, 32, s[18:19]
	v_ldexp_f32 v23, v23, v24
	v_log_f32_e32 v23, v23
	v_sub_f32_e32 v18, v18, v22
	v_mul_f32_e64 v24, |v20|, s33
	v_exp_f32_e32 v24, v24
	v_mul_f32_e32 v22, 0x3f317217, v23
	v_fma_f32 v22, v23, s2, -v22
	v_fmac_f32_e32 v22, 0x3377d1cf, v23
	v_fmac_f32_e32 v22, 0x3f317217, v23
	v_cmp_lt_f32_e64 s[20:21], |v23|, s83
	v_min_f32_e32 v20, 0, v20
	v_mul_f32_e32 v18, 0x3d800000, v18
	v_cndmask_b32_e64 v22, v23, v22, s[20:21]
	v_cndmask_b32_e64 v23, 0, v241, s[18:19]
	v_sub_f32_e32 v22, v22, v23
	v_add_f32_e32 v23, 1.0, v24
	v_cmp_gt_f32_e64 s[18:19], s68, v23
	v_sub_f32_e32 v19, v19, v22
	v_mul_f32_e32 v19, 0x3d800000, v19
	v_cndmask_b32_e64 v24, 0, 32, s[18:19]
	v_ldexp_f32 v23, v23, v24
	v_log_f32_e32 v23, v23
	v_mul_f32_e64 v24, |v21|, s33
	v_exp_f32_e32 v24, v24
	v_min_f32_e32 v21, 0, v21
	v_mul_f32_e32 v22, 0x3f317217, v23
	v_fma_f32 v22, v23, s2, -v22
	v_fmac_f32_e32 v22, 0x3377d1cf, v23
	v_fmac_f32_e32 v22, 0x3f317217, v23
	v_cmp_lt_f32_e64 s[20:21], |v23|, s83
	v_cvt_pk_bf16_f32 v18, v18, v19
	v_or_b32_e32 v40, 33, v61
	s_nop 0
	v_cndmask_b32_e64 v22, v23, v22, s[20:21]
	v_cndmask_b32_e64 v23, 0, v241, s[18:19]
	v_sub_f32_e32 v22, v22, v23
	v_add_f32_e32 v23, 1.0, v24
	v_cmp_gt_f32_e64 s[18:19], s68, v23
	v_sub_f32_e32 v20, v20, v22
	v_mul_f32_e32 v20, 0x3d800000, v20
	v_cndmask_b32_e64 v24, 0, 32, s[18:19]
	v_ldexp_f32 v23, v23, v24
	v_log_f32_e32 v23, v23
	s_nop 0
	v_mul_f32_e32 v22, 0x3f317217, v23
	v_fma_f32 v22, v23, s2, -v22
	v_fmac_f32_e32 v22, 0x3377d1cf, v23
	v_fmac_f32_e32 v22, 0x3f317217, v23
	v_cmp_lt_f32_e64 s[20:21], |v23|, s83
	s_nop 1
	v_cndmask_b32_e64 v22, v23, v22, s[20:21]
	v_cndmask_b32_e64 v23, 0, v241, s[18:19]
	v_sub_f32_e32 v22, v22, v23
	v_sub_f32_e32 v21, v21, v22
	v_mul_f32_e32 v21, 0x3d800000, v21
	v_cvt_pk_bf16_f32 v19, v20, v21
	v_mad_i32_i24 v20, v63, 48, v56
	v_mul_lo_u32 v20, v20, s55
	v_add_u32_e32 v20, 0, v20
	v_lshlrev_b32_e32 v21, 5, v77
	v_add3_u32 v20, v20, v21, v61
	ds_write_b64 v20, v[18:19]
	v_or_b32_e32 v19, v69, v43
	v_add_u32_e32 v18, 0, v0
	v_lshl_or_b32 v21, v74, 4, v43
	v_cmp_le_i32_e64 s[18:19], v61, v19
	v_add_u32_e32 v20, 2, v74
	v_mad_i32_i24 v28, v21, s55, v18
	v_cndmask_b32_e64 v21, 0, 1, s[18:19]
	v_cmp_ge_i32_e64 s[18:19], v61, v19
	s_waitcnt lgkmcnt(0)
	s_barrier
	s_lshr_b32 s101, s89, 7
	s_lshl_b32 s101, s101, 4
	v_add_u32_e32 v160, s101, v43
	v_sub_u32_e32 v160, v160, v61
	v_subrev_u32_e32 v161, 32, v160
	v_lshlrev_b32_e32 v160, 4, v160
	v_lshlrev_b32_e32 v161, 4, v161
	v_mov_b32_e32 v166, 0x3f803f80
	v_mov_b32_e32 v167, 0
	s_bitcmp1_b32 s89, 6
	s_cbranch_scc1 .Ltri_dir1_g1
	v_sub_u32_e32 v162, 16, v160
	v_med3_i32 v162, v162, 0, 32
	v_lshrrev_b64 v[164:165], v162, v[166:167]
	v_mov_b32_e32 v152, v164
	v_sub_u32_e32 v162, 48, v160
	v_med3_i32 v162, v162, 0, 32
	v_lshrrev_b64 v[164:165], v162, v[166:167]
	v_mov_b32_e32 v153, v164
	v_sub_u32_e32 v162, 0x50, v160
	v_med3_i32 v162, v162, 0, 32
	v_lshrrev_b64 v[164:165], v162, v[166:167]
	v_mov_b32_e32 v154, v164
	v_sub_u32_e32 v162, 0x70, v160
	v_med3_i32 v162, v162, 0, 32
	v_lshrrev_b64 v[164:165], v162, v[166:167]
	v_mov_b32_e32 v155, v164
	v_sub_u32_e32 v162, 16, v161
	v_med3_i32 v162, v162, 0, 32
	v_lshrrev_b64 v[164:165], v162, v[166:167]
	v_mov_b32_e32 v156, v164
	v_sub_u32_e32 v162, 48, v161
	v_med3_i32 v162, v162, 0, 32
	v_lshrrev_b64 v[164:165], v162, v[166:167]
	v_mov_b32_e32 v157, v164
	v_sub_u32_e32 v162, 0x50, v161
	v_med3_i32 v162, v162, 0, 32
	v_lshrrev_b64 v[164:165], v162, v[166:167]
	v_mov_b32_e32 v158, v164
	v_sub_u32_e32 v162, 0x70, v161
	v_med3_i32 v162, v162, 0, 32
	v_lshrrev_b64 v[164:165], v162, v[166:167]
	v_mov_b32_e32 v159, v164
	s_branch .Ltri_done_g1

; #define LAS __attribute__((address_space(3)))
; __device__ __forceinline__ unsigned pk_bf16(float lo, float hi) { unsigned r; asm volatile("v_cvt_pk_bf16_f32 %0, %1, %2" : "=v"(r) : "v"(lo), "v"(hi)); return r; }
; __device__ __forceinline__ f32x4 mfma16(bf16x8 a, bf16x8 b, f32x4 c) { return __builtin_amdgcn_mfma_f32_16x16x32_bf16(a, b, c, 0, 0, 0); }
; __device__ __forceinline__ void gla_prep(const PrepRegs& R, LAS unsigned char* lds, int wave, int fr, int fq) {
;     ...
;     for (int q = 0; q < 3; ++q) { const int tile = wave * 3 + q, mi = tile / 6, ni = tile % 6, dir = ni / 3, c = (ni % 3) * 16 + fr;
;         const f32x4 acc = mfma16(as_bf8(R.ga[q]), as_bf8(R.bw[q]), (f32x4){0.f, 0.f, 0.f, 0.f});
;         float g[4];
; #pragma unroll
;         for (int i = 0; i < 4; ++i) { const float sv = acc[i] + R.bias[q]; g[i] = (fminf(sv, 0.f) - __logf(1.f + __expf(-fabsf(sv)))) * (1.0f / 16.0f); }
;         u32x2 w2; w2.x = pk_bf16(g[0], g[1]); w2.y = pk_bf16(g[2], g[3]);
;         *(LAS u32x2*)(lds + GL_GT + (dir * 48 + c) * 144 + (mi * 16 + fq * 4) * 2) = w2; }
; __device__ __forceinline__ void gla_g3_item(int wv, const Params& p, int l, int b, int n, int h, LAS unsigned char* lds) {
;     ...
;     { const bf16_t* gp = Z + (size_t)(row0 + tf) * ZLD + ZC_GG + h * 96 + part * 12;
; #pragma unroll
;       for (int q4 = 0; q4 < 3; ++q4) ggw[q4] = *(const u32x2*)(gp + q4 * 4); }
.LBB0_991:
	s_or_b64 exec, exec, s[4:5]
	v_and_b32_e32 v59, 7, v83
	v_add_u32_e32 v58, s3, v63
	v_mov_b64_e32 v[60:61], s[36:37]
	v_mad_i64_i32 v[60:61], s[4:5], v58, s86, v[60:61]
	s_lshl_b32 s56, s34, 1
	v_mul_u32_u24_e32 v65, 12, v59
	v_lshl_add_u64 v[106:107], v[60:61], 0, s[56:57]
	v_lshlrev_b32_e32 v60, 1, v65
	v_mov_b32_e32 v61, v1
	v_lshl_add_u64 v[110:111], v[106:107], 0, v[60:61]
	s_waitcnt vmcnt(1)
	v_cvt_pk_bf16_f32 v46, v113, v112
	v_cvt_pk_bf16_f32 v47, v115, v114
	v_cvt_pk_bf16_f32 v48, v117, v116
	v_cvt_pk_bf16_f32 v49, v119, v118
	v_and_b32_e32 v46, v140, v46
	v_and_b32_e32 v47, v140, v47
	v_and_b32_e32 v48, v140, v48
	v_and_b32_e32 v49, v140, v49
	v_cvt_pk_bf16_f32 v50, v121, v120
	v_cvt_pk_bf16_f32 v51, v123, v122
	v_cvt_pk_bf16_f32 v52, v125, v124
	v_cvt_pk_bf16_f32 v53, v127, v126
	v_and_b32_e32 v50, v141, v50
	v_and_b32_e32 v51, v141, v51
	v_and_b32_e32 v52, v141, v52
	v_and_b32_e32 v53, v141, v53
	v_cvt_pk_bf16_f32 v54, v133, v132
	v_cvt_pk_bf16_f32 v55, v135, v134
	v_cvt_pk_bf16_f32 v56, v137, v136
	v_cvt_pk_bf16_f32 v57, v139, v138
	v_and_b32_e32 v54, v142, v54
	v_and_b32_e32 v55, v142, v55
	v_and_b32_e32 v56, v142, v56
	v_and_b32_e32 v57, v142, v57
	v_mfma_f32_16x16x32_bf16 v[106:109], v[6:9], v[46:49], 0
	s_waitcnt vmcnt(3)
	v_mfma_f32_16x16x32_bf16 v[38:41], v[38:41], v[50:53], 0
	v_lshlrev_b32_e32 v52, 5, v100
	s_nop 4
	v_add_f32_e32 v48, v103, v106
	v_mul_f32_e64 v6, |v48|, s33
	v_exp_f32_e32 v49, v6
	v_add_f32_e32 v61, v103, v107
	v_mul_f32_e64 v106, |v61|, s33
	v_exp_f32_e32 v106, v106
	v_add_f32_e32 v49, 1.0, v49
	v_cmp_gt_f32_e64 s[24:25], s68, v49
	v_min_f32_e32 v48, 0, v48
	s_waitcnt vmcnt(2)
	v_add_f32_e32 v38, v104, v38
	v_cndmask_b32_e64 v59, 0, 32, s[24:25]
	v_ldexp_f32 v49, v49, v59
	v_log_f32_e32 v49, v49
	v_mul_f32_e64 v50, |v38|, s33
	v_exp_f32_e32 v50, v50
	global_load_dwordx2 v[46:47], v[110:111], off offset:2320
	global_load_dwordx4 v[6:9], v[110:111], off offset:2304
	v_mul_f32_e32 v59, 0x3f317217, v49
	v_fma_f32 v59, v49, s2, -v59
	v_fmac_f32_e32 v59, 0x3377d1cf, v49
	v_fmac_f32_e32 v59, 0x3f317217, v49
	v_cmp_lt_f32_e64 s[26:27], |v49|, s83
	v_add_f32_e32 v50, 1.0, v50
	s_nop 0
	v_cndmask_b32_e64 v49, v49, v59, s[26:27]
	v_cndmask_b32_e64 v59, 0, v241, s[24:25]
	v_sub_f32_e32 v49, v49, v59
	v_add_f32_e32 v59, 1.0, v106
	v_cmp_gt_f32_e64 s[24:25], s68, v59
	v_sub_f32_e32 v48, v48, v49
	v_min_f32_e32 v49, 0, v61
	v_cndmask_b32_e64 v106, 0, 32, s[24:25]
	v_ldexp_f32 v59, v59, v106
	v_log_f32_e32 v59, v59
	v_add_f32_e32 v106, v103, v108
	v_mul_f32_e64 v107, |v106|, s33
	v_exp_f32_e32 v107, v107
	v_mul_f32_e32 v61, 0x3f317217, v59
	v_fma_f32 v61, v59, s2, -v61
	v_fmac_f32_e32 v61, 0x3377d1cf, v59
	v_fmac_f32_e32 v61, 0x3f317217, v59
	v_cmp_lt_f32_e64 s[26:27], |v59|, s83
	v_add_f32_e32 v103, v103, v109
	v_mul_f32_e32 v48, 0x3d800000, v48
	v_cndmask_b32_e64 v59, v59, v61, s[26:27]
	v_cndmask_b32_e64 v61, 0, v241, s[24:25]
	v_sub_f32_e32 v59, v59, v61
	v_add_f32_e32 v61, 1.0, v107
	v_cmp_gt_f32_e64 s[24:25], s68, v61
	v_sub_f32_e32 v49, v49, v59
	v_min_f32_e32 v59, 0, v106
	v_cndmask_b32_e64 v107, 0, 32, s[24:25]
	v_ldexp_f32 v61, v61, v107
	v_log_f32_e32 v61, v61
	v_mul_f32_e64 v107, |v103|, s33
	v_exp_f32_e32 v107, v107
	v_mul_f32_e32 v49, 0x3d800000, v49
	v_mul_f32_e32 v106, 0x3f317217, v61
	v_fma_f32 v106, v61, s2, -v106
	v_fmac_f32_e32 v106, 0x3377d1cf, v61
	v_fmac_f32_e32 v106, 0x3f317217, v61
	v_cmp_lt_f32_e64 s[26:27], |v61|, s83
	s_barrier
	s_nop 0
	v_cndmask_b32_e64 v61, v61, v106, s[26:27]
	v_cndmask_b32_e64 v106, 0, v241, s[24:25]
	v_sub_f32_e32 v61, v61, v106
	v_add_f32_e32 v106, 1.0, v107
	v_cmp_gt_f32_e64 s[24:25], s68, v106
	v_sub_f32_e32 v59, v59, v61
	v_min_f32_e32 v61, 0, v103
	v_cndmask_b32_e64 v107, 0, 32, s[24:25]
	v_ldexp_f32 v106, v106, v107
	v_log_f32_e32 v106, v106
	v_mul_f32_e32 v59, 0x3d800000, v59
	v_cvt_pk_bf16_f32 v48, v48, v49
	v_add_f32_e32 v39, v104, v39
	v_mul_f32_e32 v103, 0x3f317217, v106
	v_fma_f32 v103, v106, s2, -v103
	v_fmac_f32_e32 v103, 0x3377d1cf, v106
	v_fmac_f32_e32 v103, 0x3f317217, v106
	v_cmp_lt_f32_e64 s[26:27], |v106|, s83
	v_min_f32_e32 v38, 0, v38
	v_add_f32_e32 v40, v104, v40
	v_cndmask_b32_e64 v103, v106, v103, s[26:27]
	v_cndmask_b32_e64 v106, 0, v241, s[24:25]
	v_sub_f32_e32 v103, v103, v106
	v_sub_f32_e32 v61, v61, v103
	v_cmp_gt_f32_e64 s[24:25], s68, v50
	v_mul_f32_e32 v61, 0x3d800000, v61
	v_cvt_pk_bf16_f32 v49, v59, v61
	v_mad_i32_i24 v59, v94, 48, v74
	v_cndmask_b32_e64 v53, 0, 32, s[24:25]
	v_mul_lo_u32 v51, v59, s55
	v_ldexp_f32 v50, v50, v53
	v_add_u32_e32 v51, 0, v51
	v_log_f32_e32 v50, v50
	v_add3_u32 v51, v51, v52, v84
	ds_write_b64 v51, v[48:49]
	v_mul_f32_e64 v49, |v39|, s33
	v_exp_f32_e32 v49, v49
	v_mul_f32_e32 v48, 0x3f317217, v50
	v_fma_f32 v48, v50, s2, -v48
	v_fmac_f32_e32 v48, 0x3377d1cf, v50
	v_fmac_f32_e32 v48, 0x3f317217, v50
	v_cmp_lt_f32_e64 s[26:27], |v50|, s83
	v_add_f32_e32 v49, 1.0, v49
	v_min_f32_e32 v39, 0, v39
	v_cndmask_b32_e64 v48, v50, v48, s[26:27]
	v_cndmask_b32_e64 v50, 0, v241, s[24:25]
	v_cmp_gt_f32_e64 s[24:25], s68, v49
	v_sub_f32_e32 v48, v48, v50
	v_sub_f32_e32 v38, v38, v48
	v_cndmask_b32_e64 v50, 0, 32, s[24:25]
	v_ldexp_f32 v49, v49, v50
	v_log_f32_e32 v49, v49
	v_mul_f32_e64 v50, |v40|, s33
	v_exp_f32_e32 v50, v50
	v_add_f32_e32 v41, v104, v41
	v_mul_f32_e32 v48, 0x3f317217, v49
	v_fma_f32 v48, v49, s2, -v48
	v_fmac_f32_e32 v48, 0x3377d1cf, v49
	v_fmac_f32_e32 v48, 0x3f317217, v49
	v_cmp_lt_f32_e64 s[26:27], |v49|, s83
	v_min_f32_e32 v40, 0, v40
	v_mul_f32_e32 v38, 0x3d800000, v38
	v_cndmask_b32_e64 v48, v49, v48, s[26:27]
	v_cndmask_b32_e64 v49, 0, v241, s[24:25]
	v_sub_f32_e32 v48, v48, v49
; #define LAS __attribute__((address_space(3)))
; __device__ __forceinline__ unsigned pk_bf16(float lo, float hi) { unsigned r; asm volatile("v_cvt_pk_bf16_f32 %0, %1, %2" : "=v"(r) : "v"(lo), "v"(hi)); return r; }
; __device__ __forceinline__ f32x4 mfma16(bf16x8 a, bf16x8 b, f32x4 c) { return __builtin_amdgcn_mfma_f32_16x16x32_bf16(a, b, c, 0, 0, 0); }
; __device__ __forceinline__ void gla_prep(const PrepRegs& R, LAS unsigned char* lds, int wave, int fr, int fq) {
;     ...
;     for (int q = 0; q < 3; ++q) { const int tile = wave * 3 + q, mi = tile / 6, ni = tile % 6, dir = ni / 3, c = (ni % 3) * 16 + fr;
;         const f32x4 acc = mfma16(as_bf8(R.ga[q]), as_bf8(R.bw[q]), (f32x4){0.f, 0.f, 0.f, 0.f});
;         float g[4];
; #pragma unroll
;         for (int i = 0; i < 4; ++i) { const float sv = acc[i] + R.bias[q]; g[i] = (fminf(sv, 0.f) - __logf(1.f + __expf(-fabsf(sv)))) * (1.0f / 16.0f); }
;         u32x2 w2; w2.x = pk_bf16(g[0], g[1]); w2.y = pk_bf16(g[2], g[3]);
;         *(LAS u32x2*)(lds + GL_GT + (dir * 48 + c) * 144 + (mi * 16 + fq * 4) * 2) = w2; }
;     __syncthreads();
; #pragma unroll
;     for (int q = 0; q < 3; ++q) { const int tile = wave * 3 + q, mi = tile / 6, ni = tile % 6, dir = ni / 3;
;         f32x4 acc = (f32x4){0.f, 0.f, 0.f, 0.f};
; #pragma unroll
;         for (int kk = 0; kk < 2; ++kk) { const int t = mi * 16 + fr; bf16x8 tri;
; #pragma unroll
;             for (int e = 0; e < 8; ++e) { const int sidx = kk * 32 + fq * 8 + e; tri[e] = (dir ? (sidx >= t) : (sidx <= t)) ? (short)0x3F80 : (short)0; }
	v_add_f32_e32 v49, 1.0, v50
	v_cmp_gt_f32_e64 s[24:25], s68, v49
	v_sub_f32_e32 v39, v39, v48
	v_mul_f32_e32 v39, 0x3d800000, v39
	v_cndmask_b32_e64 v50, 0, 32, s[24:25]
	v_ldexp_f32 v49, v49, v50
	v_log_f32_e32 v49, v49
	v_mul_f32_e64 v50, |v41|, s33
	v_exp_f32_e32 v50, v50
	v_min_f32_e32 v41, 0, v41
	v_mul_f32_e32 v48, 0x3f317217, v49
	v_fma_f32 v48, v49, s2, -v48
	v_fmac_f32_e32 v48, 0x3377d1cf, v49
	v_fmac_f32_e32 v48, 0x3f317217, v49
	v_cmp_lt_f32_e64 s[26:27], |v49|, s83
	v_or_b32_e32 v59, 3, v84
	v_or_b32_e32 v61, 4, v84
	v_cndmask_b32_e64 v48, v49, v48, s[26:27]
	v_cndmask_b32_e64 v49, 0, v241, s[24:25]
	v_sub_f32_e32 v48, v48, v49
	v_add_f32_e32 v49, 1.0, v50
	v_cmp_gt_f32_e64 s[24:25], s68, v49
	v_sub_f32_e32 v40, v40, v48
	v_mul_f32_e32 v40, 0x3d800000, v40
	v_cndmask_b32_e64 v50, 0, 32, s[24:25]
	v_ldexp_f32 v49, v49, v50
	v_log_f32_e32 v49, v49
	v_mad_i32_i24 v50, v89, 48, v76
	v_or_b32_e32 v74, 5, v84
	v_or_b32_e32 v76, 6, v84
	v_mul_f32_e32 v48, 0x3f317217, v49
	v_fma_f32 v48, v49, s2, -v48
	v_fmac_f32_e32 v48, 0x3377d1cf, v49
	v_fmac_f32_e32 v48, 0x3f317217, v49
	v_cmp_lt_f32_e64 s[26:27], |v49|, s83
	v_or_b32_e32 v100, 34, v84
	v_or_b32_e32 v103, 36, v84
	v_cndmask_b32_e64 v48, v49, v48, s[26:27]
	v_cndmask_b32_e64 v49, 0, v241, s[24:25]
	v_sub_f32_e32 v48, v48, v49
	v_sub_f32_e32 v41, v41, v48
	v_mul_f32_e32 v41, 0x3d800000, v41
	v_cvt_pk_bf16_f32 v48, v38, v39
	v_cvt_pk_bf16_f32 v49, v40, v41
	s_waitcnt vmcnt(3)
	v_mfma_f32_16x16x32_bf16 v[38:41], v[42:45], v[54:57], 0
	v_mul_lo_u32 v43, v50, s55
	v_add_u32_e32 v43, 0, v43
	v_lshlrev_b32_e32 v44, 5, v101
	v_add3_u32 v43, v43, v44, v84
	ds_write_b64 v43, v[48:49]
	s_waitcnt vmcnt(2)
	s_nop 1
	v_add_f32_e32 v38, v105, v38
	v_mul_f32_e64 v42, |v38|, s33
	v_exp_f32_e32 v42, v42
	v_add_f32_e32 v39, v105, v39
	v_mul_f32_e64 v44, |v39|, s33
	v_exp_f32_e32 v44, v44
	v_add_f32_e32 v42, 1.0, v42
	v_cmp_gt_f32_e64 s[24:25], s68, v42
	v_min_f32_e32 v38, 0, v38
	v_add_f32_e32 v40, v105, v40
	v_cndmask_b32_e64 v45, 0, 32, s[24:25]
	v_ldexp_f32 v42, v42, v45
	v_log_f32_e32 v42, v42
	v_min_f32_e32 v39, 0, v39
	v_add_f32_e32 v41, v105, v41
	v_or_b32_e32 v56, 1, v84
	v_mul_f32_e32 v43, 0x3f317217, v42
	v_fma_f32 v43, v42, s2, -v43
	v_fmac_f32_e32 v43, 0x3377d1cf, v42
	v_fmac_f32_e32 v43, 0x3f317217, v42
	v_cmp_lt_f32_e64 s[26:27], |v42|, s83
	v_or_b32_e32 v57, 2, v84
	v_or_b32_e32 v101, 35, v84
	v_cndmask_b32_e64 v42, v42, v43, s[26:27]
	v_cndmask_b32_e64 v43, 0, v241, s[24:25]
	v_sub_f32_e32 v42, v42, v43
	v_add_f32_e32 v43, 1.0, v44
	v_cmp_gt_f32_e64 s[24:25], s68, v43
	v_sub_f32_e32 v38, v38, v42
	v_mul_f32_e32 v38, 0x3d800000, v38
	v_cndmask_b32_e64 v44, 0, 32, s[24:25]
	v_ldexp_f32 v43, v43, v44
	v_log_f32_e32 v43, v43
	v_mul_f32_e64 v44, |v40|, s33
	v_exp_f32_e32 v44, v44
	v_min_f32_e32 v40, 0, v40
	v_mul_f32_e32 v42, 0x3f317217, v43
	v_fma_f32 v42, v43, s2, -v42
	v_fmac_f32_e32 v42, 0x3377d1cf, v43
	v_fmac_f32_e32 v42, 0x3f317217, v43
	v_cmp_lt_f32_e64 s[26:27], |v43|, s83
	v_or_b32_e32 v104, 37, v84
	v_or_b32_e32 v106, 38, v84
	v_cndmask_b32_e64 v42, v43, v42, s[26:27]
	v_cndmask_b32_e64 v43, 0, v241, s[24:25]
	v_sub_f32_e32 v42, v42, v43
	v_add_f32_e32 v43, 1.0, v44
	v_cmp_gt_f32_e64 s[24:25], s68, v43
	v_sub_f32_e32 v39, v39, v42
	v_mul_f32_e32 v39, 0x3d800000, v39
	v_cndmask_b32_e64 v44, 0, 32, s[24:25]
	v_ldexp_f32 v43, v43, v44
	v_log_f32_e32 v43, v43
	v_mul_f32_e64 v44, |v41|, s33
	v_exp_f32_e32 v44, v44
	v_min_f32_e32 v41, 0, v41
	v_mul_f32_e32 v42, 0x3f317217, v43
	v_fma_f32 v42, v43, s2, -v42
	v_fmac_f32_e32 v42, 0x3377d1cf, v43
	v_fmac_f32_e32 v42, 0x3f317217, v43
	v_cmp_lt_f32_e64 s[26:27], |v43|, s83
	v_cvt_pk_bf16_f32 v38, v38, v39
	s_nop 1
	v_cndmask_b32_e64 v42, v43, v42, s[26:27]
	v_cndmask_b32_e64 v43, 0, v241, s[24:25]
	v_sub_f32_e32 v42, v42, v43
	v_add_f32_e32 v43, 1.0, v44
	v_cmp_gt_f32_e64 s[24:25], s68, v43
	v_sub_f32_e32 v40, v40, v42
	v_mul_f32_e32 v40, 0x3d800000, v40
	v_cndmask_b32_e64 v44, 0, 32, s[24:25]
	v_ldexp_f32 v43, v43, v44
	v_log_f32_e32 v43, v43
	s_nop 0
	v_mul_f32_e32 v42, 0x3f317217, v43
	v_fma_f32 v42, v43, s2, -v42
	v_fmac_f32_e32 v42, 0x3377d1cf, v43
	v_fmac_f32_e32 v42, 0x3f317217, v43
	v_cmp_lt_f32_e64 s[26:27], |v43|, s83
	s_nop 1
	v_cndmask_b32_e64 v42, v43, v42, s[26:27]
	v_cndmask_b32_e64 v43, 0, v241, s[24:25]
	v_sub_f32_e32 v42, v42, v43
	v_sub_f32_e32 v41, v41, v42
	v_mul_f32_e32 v41, 0x3d800000, v41
	v_cvt_pk_bf16_f32 v39, v40, v41
	v_mad_i32_i24 v40, v77, 48, v78
	v_mul_lo_u32 v40, v40, s55
	v_add_u32_e32 v40, 0, v40
	v_lshlrev_b32_e32 v41, 5, v102
	v_add3_u32 v40, v40, v41, v84
	ds_write_b64 v40, v[38:39]
	v_or_b32_e32 v39, v93, v81
	v_add_u32_e32 v38, 0, v0
	v_lshl_or_b32 v41, v99, 4, v81
	v_cmp_le_i32_e64 s[24:25], v84, v39
	v_add_u32_e32 v40, 2, v99
	v_mad_i32_i24 v44, v41, s55, v38
	v_cndmask_b32_e64 v41, 0, 1, s[24:25]
	v_cmp_ge_i32_e64 s[24:25], v84, v39
	v_or_b32_e32 v78, 7, v84
	s_waitcnt lgkmcnt(0)
	v_cndmask_b32_e64 v42, 0, 1, s[24:25]
	v_cmp_gt_u32_e64 s[24:25], 5, v40
	s_barrier
	s_lshr_b32 s101, s89, 7
	s_lshl_b32 s101, s101, 4
	v_add_u32_e32 v160, s101, v81
	v_sub_u32_e32 v160, v160, v84
	v_subrev_u32_e32 v161, 32, v160
	v_lshlrev_b32_e32 v160, 4, v160
	v_lshlrev_b32_e32 v161, 4, v161
	v_mov_b32_e32 v166, 0x3f803f80
	v_mov_b32_e32 v167, 0
	s_bitcmp1_b32 s89, 6
	s_cbranch_scc1 .Ltri_dir1_g3
	v_sub_u32_e32 v162, 16, v160
	v_med3_i32 v162, v162, 0, 32
	v_lshrrev_b64 v[164:165], v162, v[166:167]
	v_mov_b32_e32 v152, v164
	v_sub_u32_e32 v162, 48, v160
	v_med3_i32 v162, v162, 0, 32
	v_lshrrev_b64 v[164:165], v162, v[166:167]
	v_mov_b32_e32 v153, v164
	v_sub_u32_e32 v162, 0x50, v160
	v_med3_i32 v162, v162, 0, 32
	v_lshrrev_b64 v[164:165], v162, v[166:167]
	v_mov_b32_e32 v154, v164
	v_sub_u32_e32 v162, 0x70, v160
	v_med3_i32 v162, v162, 0, 32
	v_lshrrev_b64 v[164:165], v162, v[166:167]
	v_mov_b32_e32 v155, v164
	v_sub_u32_e32 v162, 16, v161
	v_med3_i32 v162, v162, 0, 32
	v_lshrrev_b64 v[164:165], v162, v[166:167]
	v_mov_b32_e32 v156, v164
	v_sub_u32_e32 v162, 48, v161
	v_med3_i32 v162, v162, 0, 32
	v_lshrrev_b64 v[164:165], v162, v[166:167]
	v_mov_b32_e32 v157, v164
	v_sub_u32_e32 v162, 0x50, v161
	v_med3_i32 v162, v162, 0, 32
	v_lshrrev_b64 v[164:165], v162, v[166:167]
	v_mov_b32_e32 v158, v164
	v_sub_u32_e32 v162, 0x70, v161
	v_med3_i32 v162, v162, 0, 32
	v_lshrrev_b64 v[164:165], v162, v[166:167]
	v_mov_b32_e32 v159, v164
	s_branch .Ltri_done_g3

; __device__ __forceinline__ unsigned pk_bf16(float lo, float hi) { unsigned r; asm volatile("v_cvt_pk_bf16_f32 %0, %1, %2" : "=v"(r) : "v"(lo), "v"(hi)); return r; }
;     __device__ __forceinline__ void operator()(const f32x4 (&acc)[2][2][4][2], const Unit& u, int wr, int wc, int fr, int fq) const {
;     ...
;             RES_LOAD(0, (size_t)row0 * 1024 + col0);
; #pragma unroll
;             for (int g = 0; g < 8; ++g) { const int ai = g >> 2, m = g & 3; const size_t off = (size_t)(row0 + ai * HALF + m * 16) * 1024 + col0;
;                 if (g < 7) { const int ai2 = (g + 1) >> 2, m2 = (g + 1) & 3; const size_t off2 = (size_t)(row0 + ai2 * HALF + m2 * 16) * 1024 + col0;
;                     if (g & 1) { RES_LOAD(0, off2); } else { RES_LOAD(1, off2); } }
;                 asm volatile("" ::: "memory");
; #pragma unroll
;                 for (int bj = 0; bj < 2; ++bj) { const f32x4 x0 = bs[g & 1][bj][0] + gv[bj][0] * acc[ai][bj][m][0], x1 = bs[g & 1][bj][1] + gv[bj][1] * acc[ai][bj][m][1];
;                     if (ob16) { u32x4 w; w.x = pk_bf16(x0[0], x0[1]); w.y = pk_bf16(x0[2], x0[3]); w.z = pk_bf16(x1[0], x1[1]); w.w = pk_bf16(x1[2], x1[3]); st16_wt((bf16_t*)u.o + off + bj * HALF, w); }
;                     else { st16_wt((float*)u.o + off + bj * HALF, __builtin_bit_cast(u32x4, x0)); st16_wt((float*)u.o + off + bj * HALF + 4, __builtin_bit_cast(u32x4, x1)); } }
.LBB0_1445:
	v_lshlrev_b64 v[138:139], 10, v[174:175]
	v_or_b32_e32 v138, v138, v184
	v_lshl_add_u64 v[130:131], v[138:139], 1, s[6:7]
	global_load_dwordx4 v[134:137], v[130:131], off
	s_nop 0
	global_load_dwordx4 v[130:133], v[130:131], off offset:256
	s_and_b64 vcc, exec, s[26:27]
	s_cbranch_vccz .Lres9_bf_w1
	s_waitcnt vmcnt(6)
	s_branch .Lres9_dn_w1
.Lres9_bf_w1:
	s_waitcnt vmcnt(4)
.Lres9_dn_w1:
	v_lshlrev_b32_e32 v140, 16, v150
	v_and_b32_e32 v141, 0xffff0000, v150
	v_lshlrev_b32_e32 v142, 16, v151
	v_and_b32_e32 v143, 0xffff0000, v151
	v_lshlrev_b32_e32 v144, 16, v152
	v_and_b32_e32 v145, 0xffff0000, v152
	v_lshlrev_b32_e32 v150, 16, v153
	v_and_b32_e32 v151, 0xffff0000, v153
	v_pk_fma_f32 v[120:121], v[120:121], v[128:129], v[142:143]
	v_pk_fma_f32 v[118:119], v[118:119], v[126:127], v[140:141]
	v_pk_fma_f32 v[116:117], v[116:117], v[124:125], v[150:151]
	v_pk_fma_f32 v[114:115], v[114:115], v[122:123], v[144:145]
	s_mov_b64 s[4:5], -1
	s_and_b64 vcc, exec, s[26:27]
	v_lshl_add_u64 v[142:143], v[176:177], 2, s[8:9]
	s_cbranch_vccz .LBB0_1447
	global_store_dwordx4 v[142:143], v[118:121], off
	global_store_dwordx4 v[142:143], v[114:117], off offset:16
	s_mov_b64 s[4:5], 0

; __device__ __forceinline__ unsigned pk_bf16(float lo, float hi) { unsigned r; asm volatile("v_cvt_pk_bf16_f32 %0, %1, %2" : "=v"(r) : "v"(lo), "v"(hi)); return r; }
;     __device__ __forceinline__ void operator()(const f32x4 (&acc)[2][2][4][2], const Unit& u, int wr, int wc, int fr, int fq) const {
;     ...
;             RES_LOAD(0, (size_t)row0 * 1024 + col0);
; #pragma unroll
;             for (int g = 0; g < 8; ++g) { const int ai = g >> 2, m = g & 3; const size_t off = (size_t)(row0 + ai * HALF + m * 16) * 1024 + col0;
;                 if (g < 7) { const int ai2 = (g + 1) >> 2, m2 = (g + 1) & 3; const size_t off2 = (size_t)(row0 + ai2 * HALF + m2 * 16) * 1024 + col0;
;                     if (g & 1) { RES_LOAD(0, off2); } else { RES_LOAD(1, off2); } }
;                 asm volatile("" ::: "memory");
; #pragma unroll
;                 for (int bj = 0; bj < 2; ++bj) { const f32x4 x0 = bs[g & 1][bj][0] + gv[bj][0] * acc[ai][bj][m][0], x1 = bs[g & 1][bj][1] + gv[bj][1] * acc[ai][bj][m][1];
;                     if (ob16) { u32x4 w; w.x = pk_bf16(x0[0], x0[1]); w.y = pk_bf16(x0[2], x0[3]); w.z = pk_bf16(x1[0], x1[1]); w.w = pk_bf16(x1[2], x1[3]); st16_wt((bf16_t*)u.o + off + bj * HALF, w); }
;                     else { st16_wt((float*)u.o + off + bj * HALF, __builtin_bit_cast(u32x4, x0)); st16_wt((float*)u.o + off + bj * HALF + 4, __builtin_bit_cast(u32x4, x1)); } }
.LBB0_1453:
	v_lshlrev_b64 v[114:115], 10, v[172:173]
	v_or_b32_e32 v114, v114, v184
	v_lshl_add_u64 v[98:99], v[114:115], 1, s[6:7]
	global_load_dwordx4 v[102:105], v[98:99], off
	s_nop 0
	global_load_dwordx4 v[98:101], v[98:99], off offset:256
	s_and_b64 vcc, exec, s[26:27]
	s_cbranch_vccz .Lres9_bf_i2
	s_waitcnt vmcnt(6)
	s_branch .Lres9_dn_i2

; __device__ __forceinline__ unsigned pk_bf16(float lo, float hi) { unsigned r; asm volatile("v_cvt_pk_bf16_f32 %0, %1, %2" : "=v"(r) : "v"(lo), "v"(hi)); return r; }
;     __device__ __forceinline__ void operator()(const f32x4 (&acc)[2][2][4][2], const Unit& u, int wr, int wc, int fr, int fq) const {
;     ...
;             RES_LOAD(0, (size_t)row0 * 1024 + col0);
; #pragma unroll
;             for (int g = 0; g < 8; ++g) { const int ai = g >> 2, m = g & 3; const size_t off = (size_t)(row0 + ai * HALF + m * 16) * 1024 + col0;
;                 if (g < 7) { const int ai2 = (g + 1) >> 2, m2 = (g + 1) & 3; const size_t off2 = (size_t)(row0 + ai2 * HALF + m2 * 16) * 1024 + col0;
;                     if (g & 1) { RES_LOAD(0, off2); } else { RES_LOAD(1, off2); } }
;                 asm volatile("" ::: "memory");
; #pragma unroll
;                 for (int bj = 0; bj < 2; ++bj) { const f32x4 x0 = bs[g & 1][bj][0] + gv[bj][0] * acc[ai][bj][m][0], x1 = bs[g & 1][bj][1] + gv[bj][1] * acc[ai][bj][m][1];
;                     if (ob16) { u32x4 w; w.x = pk_bf16(x0[0], x0[1]); w.y = pk_bf16(x0[2], x0[3]); w.z = pk_bf16(x1[0], x1[1]); w.w = pk_bf16(x1[2], x1[3]); st16_wt((bf16_t*)u.o + off + bj * HALF, w); }
;                     else { st16_wt((float*)u.o + off + bj * HALF, __builtin_bit_cast(u32x4, x0)); st16_wt((float*)u.o + off + bj * HALF + 4, __builtin_bit_cast(u32x4, x1)); } }
.Lres9_dn_i2:
	v_lshlrev_b32_e32 v116, 16, v134
	v_and_b32_e32 v117, 0xffff0000, v134
	v_lshlrev_b32_e32 v118, 16, v135
	v_and_b32_e32 v119, 0xffff0000, v135
	v_lshlrev_b32_e32 v120, 16, v136
	v_and_b32_e32 v121, 0xffff0000, v136
	v_lshlrev_b32_e32 v134, 16, v137
	v_and_b32_e32 v135, 0xffff0000, v137
	v_pk_fma_f32 v[96:97], v[96:97], v[128:129], v[118:119]
	v_pk_fma_f32 v[94:95], v[94:95], v[126:127], v[116:117]
	v_pk_fma_f32 v[92:93], v[92:93], v[124:125], v[134:135]
	v_pk_fma_f32 v[90:91], v[90:91], v[122:123], v[120:121]
	s_mov_b64 s[4:5], -1
	s_and_b64 vcc, exec, s[26:27]
	v_lshl_add_u64 v[118:119], v[138:139], 2, s[8:9]
	s_cbranch_vccz .LBB0_1455
	global_store_dwordx4 v[118:119], v[94:97], off
	global_store_dwordx4 v[118:119], v[90:93], off offset:16
	s_mov_b64 s[4:5], 0

; __device__ __forceinline__ unsigned pk_bf16(float lo, float hi) { unsigned r; asm volatile("v_cvt_pk_bf16_f32 %0, %1, %2" : "=v"(r) : "v"(lo), "v"(hi)); return r; }
;     __device__ __forceinline__ void operator()(const f32x4 (&acc)[2][2][4][2], const Unit& u, int wr, int wc, int fr, int fq) const {
;     ...
;             RES_LOAD(0, (size_t)row0 * 1024 + col0);
; #pragma unroll
;             for (int g = 0; g < 8; ++g) { const int ai = g >> 2, m = g & 3; const size_t off = (size_t)(row0 + ai * HALF + m * 16) * 1024 + col0;
;                 if (g < 7) { const int ai2 = (g + 1) >> 2, m2 = (g + 1) & 3; const size_t off2 = (size_t)(row0 + ai2 * HALF + m2 * 16) * 1024 + col0;
;                     if (g & 1) { RES_LOAD(0, off2); } else { RES_LOAD(1, off2); } }
;                 asm volatile("" ::: "memory");
; #pragma unroll
;                 for (int bj = 0; bj < 2; ++bj) { const f32x4 x0 = bs[g & 1][bj][0] + gv[bj][0] * acc[ai][bj][m][0], x1 = bs[g & 1][bj][1] + gv[bj][1] * acc[ai][bj][m][1];
;                     if (ob16) { u32x4 w; w.x = pk_bf16(x0[0], x0[1]); w.y = pk_bf16(x0[2], x0[3]); w.z = pk_bf16(x1[0], x1[1]); w.w = pk_bf16(x1[2], x1[3]); st16_wt((bf16_t*)u.o + off + bj * HALF, w); }
;                     else { st16_wt((float*)u.o + off + bj * HALF, __builtin_bit_cast(u32x4, x0)); st16_wt((float*)u.o + off + bj * HALF + 4, __builtin_bit_cast(u32x4, x1)); } }
.LBB0_1461:
	v_add_u32_e32 v90, 0x80, v170
	v_ashrrev_i32_e32 v91, 31, v90
	v_lshlrev_b64 v[92:93], 10, v[90:91]
	v_or_b32_e32 v92, v92, v184
	v_lshl_add_u64 v[82:83], v[92:93], 1, s[6:7]
	global_load_dwordx4 v[86:89], v[82:83], off
	s_nop 0
	global_load_dwordx4 v[82:85], v[82:83], off offset:256
	s_and_b64 vcc, exec, s[26:27]
	s_cbranch_vccz .Lres9_bf_w2
	s_waitcnt vmcnt(6)
	s_branch .Lres9_dn_w2

; __device__ __forceinline__ unsigned pk_bf16(float lo, float hi) { unsigned r; asm volatile("v_cvt_pk_bf16_f32 %0, %1, %2" : "=v"(r) : "v"(lo), "v"(hi)); return r; }
;     __device__ __forceinline__ void operator()(const f32x4 (&acc)[2][2][4][2], const Unit& u, int wr, int wc, int fr, int fq) const {
;     ...
;             RES_LOAD(0, (size_t)row0 * 1024 + col0);
; #pragma unroll
;             for (int g = 0; g < 8; ++g) { const int ai = g >> 2, m = g & 3; const size_t off = (size_t)(row0 + ai * HALF + m * 16) * 1024 + col0;
;                 if (g < 7) { const int ai2 = (g + 1) >> 2, m2 = (g + 1) & 3; const size_t off2 = (size_t)(row0 + ai2 * HALF + m2 * 16) * 1024 + col0;
;                     if (g & 1) { RES_LOAD(0, off2); } else { RES_LOAD(1, off2); } }
;                 asm volatile("" ::: "memory");
; #pragma unroll
;                 for (int bj = 0; bj < 2; ++bj) { const f32x4 x0 = bs[g & 1][bj][0] + gv[bj][0] * acc[ai][bj][m][0], x1 = bs[g & 1][bj][1] + gv[bj][1] * acc[ai][bj][m][1];
;                     if (ob16) { u32x4 w; w.x = pk_bf16(x0[0], x0[1]); w.y = pk_bf16(x0[2], x0[3]); w.z = pk_bf16(x1[0], x1[1]); w.w = pk_bf16(x1[2], x1[3]); st16_wt((bf16_t*)u.o + off + bj * HALF, w); }
;                     else { st16_wt((float*)u.o + off + bj * HALF, __builtin_bit_cast(u32x4, x0)); st16_wt((float*)u.o + off + bj * HALF + 4, __builtin_bit_cast(u32x4, x1)); } }
.Lres9_dn_w2:
	v_lshlrev_b32_e32 v94, 16, v102
	v_and_b32_e32 v95, 0xffff0000, v102
	v_lshlrev_b32_e32 v96, 16, v103
	v_and_b32_e32 v97, 0xffff0000, v103
	v_lshlrev_b32_e32 v102, 16, v104
	v_and_b32_e32 v103, 0xffff0000, v104
	v_lshlrev_b32_e32 v104, 16, v105
	v_and_b32_e32 v105, 0xffff0000, v105
	v_pk_fma_f32 v[80:81], v[80:81], v[128:129], v[96:97]
	v_pk_fma_f32 v[78:79], v[78:79], v[126:127], v[94:95]
	v_pk_fma_f32 v[76:77], v[76:77], v[124:125], v[104:105]
	v_pk_fma_f32 v[74:75], v[74:75], v[122:123], v[102:103]
	s_mov_b64 s[4:5], -1
	s_and_b64 vcc, exec, s[26:27]
	v_lshl_add_u64 v[96:97], v[114:115], 2, s[8:9]
	s_cbranch_vccz .LBB0_1463
	global_store_dwordx4 v[96:97], v[78:81], off
	global_store_dwordx4 v[96:97], v[74:77], off offset:16
	s_mov_b64 s[4:5], 0

; __device__ __forceinline__ unsigned pk_bf16(float lo, float hi) { unsigned r; asm volatile("v_cvt_pk_bf16_f32 %0, %1, %2" : "=v"(r) : "v"(lo), "v"(hi)); return r; }
;     __device__ __forceinline__ void operator()(const f32x4 (&acc)[2][2][4][2], const Unit& u, int wr, int wc, int fr, int fq) const {
;     ...
;             RES_LOAD(0, (size_t)row0 * 1024 + col0);
; #pragma unroll
;             for (int g = 0; g < 8; ++g) { const int ai = g >> 2, m = g & 3; const size_t off = (size_t)(row0 + ai * HALF + m * 16) * 1024 + col0;
;                 if (g < 7) { const int ai2 = (g + 1) >> 2, m2 = (g + 1) & 3; const size_t off2 = (size_t)(row0 + ai2 * HALF + m2 * 16) * 1024 + col0;
;                     if (g & 1) { RES_LOAD(0, off2); } else { RES_LOAD(1, off2); } }
;                 asm volatile("" ::: "memory");
; #pragma unroll
;                 for (int bj = 0; bj < 2; ++bj) { const f32x4 x0 = bs[g & 1][bj][0] + gv[bj][0] * acc[ai][bj][m][0], x1 = bs[g & 1][bj][1] + gv[bj][1] * acc[ai][bj][m][1];
;                     if (ob16) { u32x4 w; w.x = pk_bf16(x0[0], x0[1]); w.y = pk_bf16(x0[2], x0[3]); w.z = pk_bf16(x1[0], x1[1]); w.w = pk_bf16(x1[2], x1[3]); st16_wt((bf16_t*)u.o + off + bj * HALF, w); }
;                     else { st16_wt((float*)u.o + off + bj * HALF, __builtin_bit_cast(u32x4, x0)); st16_wt((float*)u.o + off + bj * HALF + 4, __builtin_bit_cast(u32x4, x1)); } }
.LBB0_1469:
	v_or_b32_e32 v66, 16, v90
	v_ashrrev_i32_e32 v67, 31, v66
	v_lshlrev_b64 v[74:75], 10, v[66:67]
	v_or_b32_e32 v74, v74, v184
	v_lshl_add_u64 v[66:67], v[74:75], 1, s[6:7]
	global_load_dwordx4 v[70:73], v[66:67], off
	s_nop 0
	global_load_dwordx4 v[66:69], v[66:67], off offset:256
	s_and_b64 vcc, exec, s[26:27]
	s_cbranch_vccz .Lres9_bf_i4
	s_waitcnt vmcnt(6)
	s_branch .Lres9_dn_i4

; __device__ __forceinline__ unsigned pk_bf16(float lo, float hi) { unsigned r; asm volatile("v_cvt_pk_bf16_f32 %0, %1, %2" : "=v"(r) : "v"(lo), "v"(hi)); return r; }
;     __device__ __forceinline__ void operator()(const f32x4 (&acc)[2][2][4][2], const Unit& u, int wr, int wc, int fr, int fq) const {
;     ...
;             RES_LOAD(0, (size_t)row0 * 1024 + col0);
; #pragma unroll
;             for (int g = 0; g < 8; ++g) { const int ai = g >> 2, m = g & 3; const size_t off = (size_t)(row0 + ai * HALF + m * 16) * 1024 + col0;
;                 if (g < 7) { const int ai2 = (g + 1) >> 2, m2 = (g + 1) & 3; const size_t off2 = (size_t)(row0 + ai2 * HALF + m2 * 16) * 1024 + col0;
;                     if (g & 1) { RES_LOAD(0, off2); } else { RES_LOAD(1, off2); } }
;                 asm volatile("" ::: "memory");
; #pragma unroll
;                 for (int bj = 0; bj < 2; ++bj) { const f32x4 x0 = bs[g & 1][bj][0] + gv[bj][0] * acc[ai][bj][m][0], x1 = bs[g & 1][bj][1] + gv[bj][1] * acc[ai][bj][m][1];
;                     if (ob16) { u32x4 w; w.x = pk_bf16(x0[0], x0[1]); w.y = pk_bf16(x0[2], x0[3]); w.z = pk_bf16(x1[0], x1[1]); w.w = pk_bf16(x1[2], x1[3]); st16_wt((bf16_t*)u.o + off + bj * HALF, w); }
;                     else { st16_wt((float*)u.o + off + bj * HALF, __builtin_bit_cast(u32x4, x0)); st16_wt((float*)u.o + off + bj * HALF + 4, __builtin_bit_cast(u32x4, x1)); } }
.Lres9_dn_i4:
	v_lshlrev_b32_e32 v76, 16, v86
	v_and_b32_e32 v77, 0xffff0000, v86
	v_lshlrev_b32_e32 v78, 16, v87
	v_and_b32_e32 v79, 0xffff0000, v87
	v_lshlrev_b32_e32 v80, 16, v88
	v_and_b32_e32 v81, 0xffff0000, v88
	v_lshlrev_b32_e32 v86, 16, v89
	v_and_b32_e32 v87, 0xffff0000, v89
	v_pk_fma_f32 v[64:65], v[64:65], v[128:129], v[78:79]
	v_pk_fma_f32 v[62:63], v[62:63], v[126:127], v[76:77]
	v_pk_fma_f32 v[60:61], v[60:61], v[124:125], v[86:87]
	v_pk_fma_f32 v[58:59], v[58:59], v[122:123], v[80:81]
	s_mov_b64 s[4:5], -1
	s_and_b64 vcc, exec, s[26:27]
	v_lshl_add_u64 v[78:79], v[92:93], 2, s[8:9]
	s_cbranch_vccz .LBB0_1471
	global_store_dwordx4 v[78:79], v[62:65], off
	global_store_dwordx4 v[78:79], v[58:61], off offset:16
	s_mov_b64 s[4:5], 0

; __device__ __forceinline__ unsigned pk_bf16(float lo, float hi) { unsigned r; asm volatile("v_cvt_pk_bf16_f32 %0, %1, %2" : "=v"(r) : "v"(lo), "v"(hi)); return r; }
;     __device__ __forceinline__ void operator()(const f32x4 (&acc)[2][2][4][2], const Unit& u, int wr, int wc, int fr, int fq) const {
;     ...
;             RES_LOAD(0, (size_t)row0 * 1024 + col0);
; #pragma unroll
;             for (int g = 0; g < 8; ++g) { const int ai = g >> 2, m = g & 3; const size_t off = (size_t)(row0 + ai * HALF + m * 16) * 1024 + col0;
;                 if (g < 7) { const int ai2 = (g + 1) >> 2, m2 = (g + 1) & 3; const size_t off2 = (size_t)(row0 + ai2 * HALF + m2 * 16) * 1024 + col0;
;                     if (g & 1) { RES_LOAD(0, off2); } else { RES_LOAD(1, off2); } }
;                 asm volatile("" ::: "memory");
; #pragma unroll
;                 for (int bj = 0; bj < 2; ++bj) { const f32x4 x0 = bs[g & 1][bj][0] + gv[bj][0] * acc[ai][bj][m][0], x1 = bs[g & 1][bj][1] + gv[bj][1] * acc[ai][bj][m][1];
;                     if (ob16) { u32x4 w; w.x = pk_bf16(x0[0], x0[1]); w.y = pk_bf16(x0[2], x0[3]); w.z = pk_bf16(x1[0], x1[1]); w.w = pk_bf16(x1[2], x1[3]); st16_wt((bf16_t*)u.o + off + bj * HALF, w); }
;                     else { st16_wt((float*)u.o + off + bj * HALF, __builtin_bit_cast(u32x4, x0)); st16_wt((float*)u.o + off + bj * HALF + 4, __builtin_bit_cast(u32x4, x1)); } }
.LBB0_1477:
	v_or_b32_e32 v50, 32, v90
	v_ashrrev_i32_e32 v51, 31, v50
	v_lshlrev_b64 v[58:59], 10, v[50:51]
	v_or_b32_e32 v58, v58, v184
	v_lshl_add_u64 v[50:51], v[58:59], 1, s[6:7]
	global_load_dwordx4 v[54:57], v[50:51], off
	s_nop 0
	global_load_dwordx4 v[50:53], v[50:51], off offset:256
	s_and_b64 vcc, exec, s[26:27]
	s_cbranch_vccz .Lres9_bf_w3
	s_waitcnt vmcnt(6)
	s_branch .Lres9_dn_w3

; __device__ __forceinline__ unsigned pk_bf16(float lo, float hi) { unsigned r; asm volatile("v_cvt_pk_bf16_f32 %0, %1, %2" : "=v"(r) : "v"(lo), "v"(hi)); return r; }
;     __device__ __forceinline__ void operator()(const f32x4 (&acc)[2][2][4][2], const Unit& u, int wr, int wc, int fr, int fq) const {
;     ...
;             RES_LOAD(0, (size_t)row0 * 1024 + col0);
; #pragma unroll
;             for (int g = 0; g < 8; ++g) { const int ai = g >> 2, m = g & 3; const size_t off = (size_t)(row0 + ai * HALF + m * 16) * 1024 + col0;
;                 if (g < 7) { const int ai2 = (g + 1) >> 2, m2 = (g + 1) & 3; const size_t off2 = (size_t)(row0 + ai2 * HALF + m2 * 16) * 1024 + col0;
;                     if (g & 1) { RES_LOAD(0, off2); } else { RES_LOAD(1, off2); } }
;                 asm volatile("" ::: "memory");
; #pragma unroll
;                 for (int bj = 0; bj < 2; ++bj) { const f32x4 x0 = bs[g & 1][bj][0] + gv[bj][0] * acc[ai][bj][m][0], x1 = bs[g & 1][bj][1] + gv[bj][1] * acc[ai][bj][m][1];
;                     if (ob16) { u32x4 w; w.x = pk_bf16(x0[0], x0[1]); w.y = pk_bf16(x0[2], x0[3]); w.z = pk_bf16(x1[0], x1[1]); w.w = pk_bf16(x1[2], x1[3]); st16_wt((bf16_t*)u.o + off + bj * HALF, w); }
;                     else { st16_wt((float*)u.o + off + bj * HALF, __builtin_bit_cast(u32x4, x0)); st16_wt((float*)u.o + off + bj * HALF + 4, __builtin_bit_cast(u32x4, x1)); } }
.Lres9_dn_w3:
	v_lshlrev_b32_e32 v60, 16, v70
	v_and_b32_e32 v61, 0xffff0000, v70
	v_lshlrev_b32_e32 v62, 16, v71
	v_and_b32_e32 v63, 0xffff0000, v71
	v_lshlrev_b32_e32 v64, 16, v72
	v_and_b32_e32 v65, 0xffff0000, v72
	v_lshlrev_b32_e32 v70, 16, v73
	v_and_b32_e32 v71, 0xffff0000, v73
	v_pk_fma_f32 v[48:49], v[48:49], v[128:129], v[62:63]
	v_pk_fma_f32 v[46:47], v[46:47], v[126:127], v[60:61]
	v_pk_fma_f32 v[44:45], v[44:45], v[124:125], v[70:71]
	v_pk_fma_f32 v[42:43], v[42:43], v[122:123], v[64:65]
	s_mov_b64 s[4:5], -1
	s_and_b64 vcc, exec, s[26:27]
	v_lshl_add_u64 v[62:63], v[74:75], 2, s[8:9]
	s_cbranch_vccz .LBB0_1479
	global_store_dwordx4 v[62:63], v[46:49], off
	global_store_dwordx4 v[62:63], v[42:45], off offset:16
	s_mov_b64 s[4:5], 0

; __device__ __forceinline__ unsigned pk_bf16(float lo, float hi) { unsigned r; asm volatile("v_cvt_pk_bf16_f32 %0, %1, %2" : "=v"(r) : "v"(lo), "v"(hi)); return r; }
;     __device__ __forceinline__ void operator()(const f32x4 (&acc)[2][2][4][2], const Unit& u, int wr, int wc, int fr, int fq) const {
;     ...
;             RES_LOAD(0, (size_t)row0 * 1024 + col0);
; #pragma unroll
;             for (int g = 0; g < 8; ++g) { const int ai = g >> 2, m = g & 3; const size_t off = (size_t)(row0 + ai * HALF + m * 16) * 1024 + col0;
;                 if (g < 7) { const int ai2 = (g + 1) >> 2, m2 = (g + 1) & 3; const size_t off2 = (size_t)(row0 + ai2 * HALF + m2 * 16) * 1024 + col0;
;                     if (g & 1) { RES_LOAD(0, off2); } else { RES_LOAD(1, off2); } }
;                 asm volatile("" ::: "memory");
; #pragma unroll
;                 for (int bj = 0; bj < 2; ++bj) { const f32x4 x0 = bs[g & 1][bj][0] + gv[bj][0] * acc[ai][bj][m][0], x1 = bs[g & 1][bj][1] + gv[bj][1] * acc[ai][bj][m][1];
;                     if (ob16) { u32x4 w; w.x = pk_bf16(x0[0], x0[1]); w.y = pk_bf16(x0[2], x0[3]); w.z = pk_bf16(x1[0], x1[1]); w.w = pk_bf16(x1[2], x1[3]); st16_wt((bf16_t*)u.o + off + bj * HALF, w); }
;                     else { st16_wt((float*)u.o + off + bj * HALF, __builtin_bit_cast(u32x4, x0)); st16_wt((float*)u.o + off + bj * HALF + 4, __builtin_bit_cast(u32x4, x1)); } }
.LBB0_1485:
	v_or_b32_e32 v34, 48, v90
	v_ashrrev_i32_e32 v35, 31, v34
	v_lshlrev_b64 v[42:43], 10, v[34:35]
	v_or_b32_e32 v42, v42, v184
	v_lshl_add_u64 v[34:35], v[42:43], 1, s[6:7]
	global_load_dwordx4 v[38:41], v[34:35], off
	s_nop 0
	global_load_dwordx4 v[34:37], v[34:35], off offset:256
	s_and_b64 vcc, exec, s[26:27]
	s_cbranch_vccz .Lres9_bf_i6
	s_waitcnt vmcnt(6)
	s_branch .Lres9_dn_i6

; __device__ __forceinline__ unsigned pk_bf16(float lo, float hi) { unsigned r; asm volatile("v_cvt_pk_bf16_f32 %0, %1, %2" : "=v"(r) : "v"(lo), "v"(hi)); return r; }
;     __device__ __forceinline__ void operator()(const f32x4 (&acc)[2][2][4][2], const Unit& u, int wr, int wc, int fr, int fq) const {
;     ...
;             RES_LOAD(0, (size_t)row0 * 1024 + col0);
; #pragma unroll
;             for (int g = 0; g < 8; ++g) { const int ai = g >> 2, m = g & 3; const size_t off = (size_t)(row0 + ai * HALF + m * 16) * 1024 + col0;
;                 if (g < 7) { const int ai2 = (g + 1) >> 2, m2 = (g + 1) & 3; const size_t off2 = (size_t)(row0 + ai2 * HALF + m2 * 16) * 1024 + col0;
;                     if (g & 1) { RES_LOAD(0, off2); } else { RES_LOAD(1, off2); } }
;                 asm volatile("" ::: "memory");
; #pragma unroll
;                 for (int bj = 0; bj < 2; ++bj) { const f32x4 x0 = bs[g & 1][bj][0] + gv[bj][0] * acc[ai][bj][m][0], x1 = bs[g & 1][bj][1] + gv[bj][1] * acc[ai][bj][m][1];
;                     if (ob16) { u32x4 w; w.x = pk_bf16(x0[0], x0[1]); w.y = pk_bf16(x0[2], x0[3]); w.z = pk_bf16(x1[0], x1[1]); w.w = pk_bf16(x1[2], x1[3]); st16_wt((bf16_t*)u.o + off + bj * HALF, w); }
;                     else { st16_wt((float*)u.o + off + bj * HALF, __builtin_bit_cast(u32x4, x0)); st16_wt((float*)u.o + off + bj * HALF + 4, __builtin_bit_cast(u32x4, x1)); } }
.Lres9_dn_i6:
	v_lshlrev_b32_e32 v44, 16, v54
	v_and_b32_e32 v45, 0xffff0000, v54
	v_lshlrev_b32_e32 v46, 16, v55
	v_and_b32_e32 v47, 0xffff0000, v55
	v_lshlrev_b32_e32 v48, 16, v56
	v_and_b32_e32 v49, 0xffff0000, v56
	v_lshlrev_b32_e32 v54, 16, v57
	v_and_b32_e32 v55, 0xffff0000, v57
	v_pk_fma_f32 v[32:33], v[32:33], v[128:129], v[46:47]
	v_pk_fma_f32 v[30:31], v[30:31], v[126:127], v[44:45]
	v_pk_fma_f32 v[28:29], v[28:29], v[124:125], v[54:55]
	v_pk_fma_f32 v[26:27], v[26:27], v[122:123], v[48:49]
	s_mov_b64 s[4:5], -1
	s_and_b64 vcc, exec, s[26:27]
	v_lshl_add_u64 v[46:47], v[58:59], 2, s[8:9]
	s_cbranch_vccz .LBB0_1487
	global_store_dwordx4 v[46:47], v[30:33], off
	global_store_dwordx4 v[46:47], v[26:29], off offset:16
	s_mov_b64 s[4:5], 0

; __device__ __forceinline__ unsigned pk_bf16(float lo, float hi) { unsigned r; asm volatile("v_cvt_pk_bf16_f32 %0, %1, %2" : "=v"(r) : "v"(lo), "v"(hi)); return r; }
;     __device__ __forceinline__ void operator()(const f32x4 (&acc)[2][2][4][2], const Unit& u, int wr, int wc, int fr, int fq) const {
;     ...
;             RES_LOAD(0, (size_t)row0 * 1024 + col0);
; #pragma unroll
;             for (int g = 0; g < 8; ++g) { const int ai = g >> 2, m = g & 3; const size_t off = (size_t)(row0 + ai * HALF + m * 16) * 1024 + col0;
;                 if (g < 7) { const int ai2 = (g + 1) >> 2, m2 = (g + 1) & 3; const size_t off2 = (size_t)(row0 + ai2 * HALF + m2 * 16) * 1024 + col0;
;                     if (g & 1) { RES_LOAD(0, off2); } else { RES_LOAD(1, off2); } }
;                 asm volatile("" ::: "memory");
; #pragma unroll
;                 for (int bj = 0; bj < 2; ++bj) { const f32x4 x0 = bs[g & 1][bj][0] + gv[bj][0] * acc[ai][bj][m][0], x1 = bs[g & 1][bj][1] + gv[bj][1] * acc[ai][bj][m][1];
;                     if (ob16) { u32x4 w; w.x = pk_bf16(x0[0], x0[1]); w.y = pk_bf16(x0[2], x0[3]); w.z = pk_bf16(x1[0], x1[1]); w.w = pk_bf16(x1[2], x1[3]); st16_wt((bf16_t*)u.o + off + bj * HALF, w); }
;                     else { st16_wt((float*)u.o + off + bj * HALF, __builtin_bit_cast(u32x4, x0)); st16_wt((float*)u.o + off + bj * HALF + 4, __builtin_bit_cast(u32x4, x1)); } }
.LBB0_1493:
	s_and_b64 vcc, exec, s[26:27]
	s_cbranch_vccz .Lres9_bf_w4
	s_waitcnt vmcnt(4)
	s_branch .Lres9_dn_w4
.Lres9_bf_w4:
	s_waitcnt vmcnt(2)
.Lres9_dn_w4:
	v_lshlrev_b32_e32 v18, 16, v38
	v_and_b32_e32 v19, 0xffff0000, v38
	v_lshlrev_b32_e32 v20, 16, v39
	v_and_b32_e32 v21, 0xffff0000, v39
	v_lshlrev_b32_e32 v22, 16, v40
	v_and_b32_e32 v23, 0xffff0000, v40
	v_lshlrev_b32_e32 v24, 16, v41
	v_and_b32_e32 v25, 0xffff0000, v41
	v_pk_fma_f32 v[16:17], v[16:17], v[128:129], v[20:21]
	v_pk_fma_f32 v[14:15], v[14:15], v[126:127], v[18:19]
	v_pk_fma_f32 v[12:13], v[12:13], v[124:125], v[24:25]
	v_pk_fma_f32 v[10:11], v[10:11], v[122:123], v[22:23]
	s_mov_b64 s[4:5], -1
	s_and_b64 vcc, exec, s[26:27]
	v_lshl_add_u64 v[20:21], v[42:43], 2, s[8:9]
	s_cbranch_vccz .LBB0_1495
	global_store_dwordx4 v[20:21], v[14:17], off
	global_store_dwordx4 v[20:21], v[10:13], off offset:16
	s_mov_b64 s[4:5], 0
